# v63 + sample attention: two f32 cache tiles in flight (tile T+2 issued into alternating landing register sets, counted vmcnt(8))
# speedup vs baseline: 1.0059x; 1.0045x over previous
.LBB0_1021:
	s_ashr_i32 s6, s41, 3
	s_lshl_b32 s33, s6, 4
	s_add_i32 s49, s33, 0x8000
	s_and_b32 s7, s41, 7
	v_or_b32_e32 v0, s49, v73
	v_ashrrev_i32_e32 v1, 31, v0
	s_lshl_b32 s50, s7, 7
	v_lshlrev_b64 v[0:1], 11, v[0:1]
	s_or_b32 s8, s50, s44
	v_lshl_add_u64 v[0:1], s[20:21], 0, v[0:1]
	s_lshl_b32 s38, s8, 1
	v_lshl_add_u64 v[0:1], v[0:1], 0, s[38:39]
	v_mov_b32_e32 v89, v75
	v_lshl_add_u64 v[8:9], v[0:1], 0, v[88:89]
	s_lshl_b32 s6, s6, 12
	global_load_dwordx4 v[0:3], v[8:9], off
	global_load_dwordx4 v[4:7], v[8:9], off offset:64
	v_add_u32_e32 v8, s6, v77
	v_ashrrev_i32_e32 v9, 31, v8
	v_lshlrev_b64 v[8:9], 12, v[8:9]
	v_lshl_add_u64 v[10:11], s[16:17], 0, v[8:9]
	s_lshl_b32 s38, s7, 9
	v_lshl_add_u64 v[10:11], v[10:11], 0, s[38:39]
	v_lshlrev_b32_e32 v74, 2, v76
	v_lshl_add_u64 v[8:9], s[18:19], 0, v[8:9]
	v_lshl_add_u64 v[10:11], v[10:11], 0, v[74:75]
	v_lshl_add_u64 v[8:9], v[8:9], 0, s[38:39]
	v_lshl_add_u64 v[8:9], v[8:9], 0, v[74:75]
	global_load_dwordx4 v[172:175], v[10:11], off
	global_load_dwordx4 v[168:171], v[10:11], off offset:16
	global_load_dwordx4 v[164:167], v[10:11], off offset:32
	global_load_dwordx4 v[160:163], v[10:11], off offset:48
	global_load_dwordx4 v[176:179], v[8:9], off offset:48
	global_load_dwordx4 v[180:183], v[8:9], off offset:32
	global_load_dwordx4 v[184:187], v[8:9], off offset:16
	global_load_dwordx4 v[188:191], v[8:9], off
	s_mov_b64 s[98:99], 0x40000
	v_lshl_add_u64 v[228:229], v[10:11], 0, s[98:99]
	v_lshl_add_u64 v[230:231], v[8:9], 0, s[98:99]
	global_load_dwordx4 v[192:195], v[228:229], off offset:48
	global_load_dwordx4 v[196:199], v[228:229], off offset:32
	global_load_dwordx4 v[200:203], v[228:229], off offset:16
	global_load_dwordx4 v[204:207], v[228:229], off
	global_load_dwordx4 v[208:211], v[230:231], off offset:48
	global_load_dwordx4 v[212:215], v[230:231], off offset:32
	global_load_dwordx4 v[216:219], v[230:231], off offset:16
	global_load_dwordx4 v[220:223], v[230:231], off
	v_lshl_add_u64 v[92:93], v[84:85], 0, s[38:39]
	v_lshl_add_u64 v[94:95], v[86:87], 0, s[38:39]
	v_add_u32_e32 v96, s6, v124
	v_mov_b32_e32 v91, 0xff800000
	v_mov_b32_e32 v89, 0
	s_mov_b32 s34, s39
	v_mov_b32_e32 v8, 0
	v_mov_b32_e32 v9, v75
	v_mov_b32_e32 v10, v75
	v_mov_b32_e32 v11, v75
	v_mov_b32_e32 v20, 0
	v_mov_b32_e32 v21, v75
	v_mov_b32_e32 v22, v75
	v_mov_b32_e32 v23, v75
	v_mov_b32_e32 v24, 0
	v_mov_b32_e32 v25, v75
	v_mov_b32_e32 v26, v75
	v_mov_b32_e32 v27, v75
	v_mov_b32_e32 v28, 0
	v_mov_b32_e32 v29, v75
	v_mov_b32_e32 v30, v75
	v_mov_b32_e32 v31, v75
	v_mov_b32_e32 v32, 0
	v_mov_b32_e32 v33, v75
	v_mov_b32_e32 v34, v75
	v_mov_b32_e32 v35, v75
	v_mov_b32_e32 v36, 0
	v_mov_b32_e32 v37, v75
	v_mov_b32_e32 v38, v75
	v_mov_b32_e32 v39, v75
	v_mov_b32_e32 v16, 0
	v_mov_b32_e32 v17, v75
	v_mov_b32_e32 v18, v75
	v_mov_b32_e32 v19, v75
	v_mov_b32_e32 v12, 0
	v_mov_b32_e32 v13, v75
	v_mov_b32_e32 v14, v75
	v_mov_b32_e32 v15, v75
	s_barrier
.LBB0_1022:
	s_and_b32 s6, s34, 1
	s_waitcnt vmcnt(8)
	s_bitcmp1_b32 s34, 0
	s_cbranch_scc1 .Lsa_copy1
	v_mov_b64_e32 v[60:61], v[160:161]
	v_mov_b64_e32 v[62:63], v[162:163]
	v_mov_b64_e32 v[56:57], v[164:165]
	v_mov_b64_e32 v[58:59], v[166:167]
	v_mov_b64_e32 v[64:65], v[168:169]
	v_mov_b64_e32 v[66:67], v[170:171]
	v_mov_b64_e32 v[68:69], v[172:173]
	v_mov_b64_e32 v[70:71], v[174:175]
	v_mov_b64_e32 v[40:41], v[176:177]
	v_mov_b64_e32 v[42:43], v[178:179]
	v_mov_b64_e32 v[44:45], v[180:181]
	v_mov_b64_e32 v[46:47], v[182:183]
	v_mov_b64_e32 v[48:49], v[184:185]
	v_mov_b64_e32 v[50:51], v[186:187]
	v_mov_b64_e32 v[52:53], v[188:189]
	v_mov_b64_e32 v[54:55], v[190:191]
	s_branch .Lsa_copied
.Lsa_copy1:
	v_mov_b64_e32 v[60:61], v[192:193]
	v_mov_b64_e32 v[62:63], v[194:195]
	v_mov_b64_e32 v[56:57], v[196:197]
	v_mov_b64_e32 v[58:59], v[198:199]
	v_mov_b64_e32 v[64:65], v[200:201]
	v_mov_b64_e32 v[66:67], v[202:203]
	v_mov_b64_e32 v[68:69], v[204:205]
	v_mov_b64_e32 v[70:71], v[206:207]
	v_mov_b64_e32 v[40:41], v[208:209]
	v_mov_b64_e32 v[42:43], v[210:211]
	v_mov_b64_e32 v[44:45], v[212:213]
	v_mov_b64_e32 v[46:47], v[214:215]
	v_mov_b64_e32 v[48:49], v[216:217]
	v_mov_b64_e32 v[50:51], v[218:219]
	v_mov_b64_e32 v[52:53], v[220:221]
	v_mov_b64_e32 v[54:55], v[222:223]
.Lsa_copied:
	v_cvt_pk_bf16_f32 v56, v56, v57
	v_cvt_pk_bf16_f32 v57, v58, v59
	v_cvt_pk_bf16_f32 v59, v62, v63
	v_bfe_u32 v62, v54, 16, 1
	v_bfe_u32 v63, v55, 16, 1
	v_bfe_u32 v137, v40, 16, 1
	v_bfe_u32 v138, v41, 16, 1
	v_ashrrev_i32_e32 v97, 31, v96
	s_mul_i32 s7, s6, 0x4800
	v_cvt_pk_bf16_f32 v68, v68, v69
	v_cvt_pk_bf16_f32 v69, v70, v71
	v_cvt_pk_bf16_f32 v70, v64, v65
	v_cvt_pk_bf16_f32 v58, v60, v61
	v_bfe_u32 v60, v52, 16, 1
	v_bfe_u32 v61, v53, 16, 1
	v_bfe_u32 v64, v48, 16, 1
	v_bfe_u32 v65, v49, 16, 1
	v_bfe_u32 v139, v42, 16, 1
	v_bfe_u32 v140, v43, 16, 1
	s_lshl_b32 s6, s6, 10
	v_add3_u32 v54, v54, v62, s45
	v_add3_u32 v55, v55, v63, s45
	v_add3_u32 v62, v40, v137, s45
	v_add3_u32 v63, v41, v138, s45
	v_lshlrev_b64 v[40:41], 12, v[96:97]
	s_add_i32 s7, s7, 0
	v_mov_b32_e32 v150, v89
	v_mov_b32_e32 v89, v91
	v_cvt_pk_bf16_f32 v71, v66, v67
	v_bfe_u32 v91, v44, 16, 1
	v_bfe_u32 v134, v45, 16, 1
	v_bfe_u32 v135, v46, 16, 1
	v_bfe_u32 v136, v47, 16, 1
	v_add3_u32 v60, v52, v60, s45
	v_add3_u32 v61, v53, v61, s45
	v_add3_u32 v48, v48, v64, s45
	v_add3_u32 v49, v49, v65, s45
	v_add3_u32 v64, v42, v139, s45
	v_add3_u32 v65, v43, v140, s45
	v_lshl_add_u64 v[42:43], v[92:93], 0, v[40:41]
	v_lshl_add_u64 v[52:53], v[94:95], 0, v[40:41]
	s_sub_i32 s6, s7, s6
	v_add3_u32 v40, s7, v81, v98
	v_add_u32_e32 v41, s7, v101
	v_bfe_u32 v66, v50, 16, 1
	v_bfe_u32 v67, v51, 16, 1
	v_add3_u32 v44, v44, v91, s45
	v_add3_u32 v45, v45, v134, s45
	v_add3_u32 v46, v46, v135, s45
	v_add3_u32 v47, v47, v136, s45
	ds_write_b128 v40, v[68:71]
	ds_write_b128 v40, v[56:59] offset:16
	v_add3_u32 v40, s6, v99, v106
	v_add3_u32 v91, v41, v102, s42
	v_add3_u32 v50, v50, v66, s45
	v_add3_u32 v51, v51, v67, s45
	ds_write_b16_d16_hi v40, v60 offset:36864
	ds_write_b16_d16_hi v40, v61 offset:37000
	ds_write_b16_d16_hi v40, v54 offset:37136
	ds_write_b16_d16_hi v40, v55 offset:37272
	ds_write_b16_d16_hi v40, v48 offset:37408
	ds_write_b16_d16_hi v40, v49 offset:37544
	ds_write_b16_d16_hi v40, v50 offset:37680
	ds_write_b16_d16_hi v40, v51 offset:37816
	ds_write_b16_d16_hi v40, v44 offset:37952
	ds_write_b16_d16_hi v40, v45 offset:38088
	ds_write_b16_d16_hi v40, v46 offset:38224
	ds_write_b16_d16_hi v40, v47 offset:38360
	ds_write_b16_d16_hi v40, v62 offset:38496
	ds_write_b16_d16_hi v40, v63 offset:38632
	ds_write_b16_d16_hi v40, v64 offset:38768
	ds_write_b16_d16_hi v40, v65 offset:38904
	s_waitcnt lgkmcnt(0)
	s_barrier
	s_cmp_lt_u32 s34, 62
	s_cbranch_scc0 .Lsa_noload
	v_add_u32_e32 v226, 64, v96
	v_ashrrev_i32_e32 v227, 31, v226
	v_lshlrev_b64 v[226:227], 12, v[226:227]
	v_lshl_add_u64 v[228:229], v[92:93], 0, v[226:227]
	v_lshl_add_u64 v[230:231], v[94:95], 0, v[226:227]
	s_bitcmp1_b32 s34, 0
	s_cbranch_scc1 .Lsa_load1
	global_load_dwordx4 v[160:163], v[228:229], off offset:48
	global_load_dwordx4 v[164:167], v[228:229], off offset:32
	global_load_dwordx4 v[168:171], v[228:229], off offset:16
	global_load_dwordx4 v[172:175], v[228:229], off
	global_load_dwordx4 v[176:179], v[230:231], off offset:48
	global_load_dwordx4 v[180:183], v[230:231], off offset:32
	global_load_dwordx4 v[184:187], v[230:231], off offset:16
	global_load_dwordx4 v[188:191], v[230:231], off
	s_branch .Lsa_noload
.Lsa_load1:
	global_load_dwordx4 v[192:195], v[228:229], off offset:48
	global_load_dwordx4 v[196:199], v[228:229], off offset:32
	global_load_dwordx4 v[200:203], v[228:229], off offset:16
	global_load_dwordx4 v[204:207], v[228:229], off
	global_load_dwordx4 v[208:211], v[230:231], off offset:48
	global_load_dwordx4 v[212:215], v[230:231], off offset:32
	global_load_dwordx4 v[216:219], v[230:231], off offset:16
	global_load_dwordx4 v[220:223], v[230:231], off
.Lsa_noload:
	ds_read_b128 v[134:137], v91
	s_nop 0
	ds_read_b128 v[138:141], v91 offset:64
	s_nop 0
	s_waitcnt lgkmcnt(1)
	v_mfma_f32_16x16x32_bf16 v[134:137], v[134:137], v[0:3], 0
	s_add_i32 s6, s43, s6
	v_add3_u32 v97, s6, v72, v107
	ds_read_b64 v[142:143], v97 offset:36864
	s_waitcnt lgkmcnt(1)
	v_mfma_f32_16x16x32_bf16 v[134:137], v[138:141], v[4:7], v[134:137]
	ds_read_b64 v[144:145], v97 offset:39040
	ds_read_b64 v[146:147], v97 offset:41216
	ds_read_b64 v[148:149], v97 offset:43392
	s_add_i32 s34, s34, 1
	v_add_u32_e32 v96, 64, v96
	s_nop 2
	v_max_f32_e32 v91, v137, v137
	v_max_f32_e32 v138, v136, v136
	v_max_f32_e32 v91, v138, v91
	v_max3_f32 v91, v134, v135, v91
	ds_bpermute_b32 v138, v103, v91
	s_cmp_eq_u32 s34, 63
	s_waitcnt lgkmcnt(0)
	v_max_f32_e32 v138, v138, v138
	v_max_f32_e32 v91, v91, v138
	ds_bpermute_b32 v138, v104, v91
	s_waitcnt lgkmcnt(0)
	v_max3_f32 v91, v89, v91, v138
	v_sub_f32_e32 v89, v89, v91
	v_sub_f32_e32 v134, v134, v91
	v_sub_f32_e32 v135, v135, v91
	v_sub_f32_e32 v136, v136, v91
	v_sub_f32_e32 v137, v137, v91
	v_cmp_gt_f32_e32 vcc, s46, v89
	v_cmp_gt_f32_e64 s[6:7], s46, v134
	v_cmp_gt_f32_e64 s[8:9], s46, v135
	v_cmp_gt_f32_e64 s[10:11], s46, v136
	v_cmp_gt_f32_e64 s[12:13], s46, v137
	v_cndmask_b32_e32 v138, 0, v130, vcc
	v_cndmask_b32_e64 v139, 0, v130, s[6:7]
	v_cndmask_b32_e64 v140, 0, v130, s[8:9]
	v_cndmask_b32_e64 v141, 0, v130, s[10:11]
	v_cndmask_b32_e64 v151, 0, v130, s[12:13]
	v_add_f32_e32 v89, v89, v138
	v_add_f32_e32 v134, v134, v139
	v_add_f32_e32 v135, v135, v140
	v_add_f32_e32 v136, v136, v141
	v_add_f32_e32 v137, v137, v151
	v_exp_f32_e32 v89, v89
	v_exp_f32_e32 v152, v134
	v_exp_f32_e32 v135, v135
	v_exp_f32_e32 v153, v136
	v_exp_f32_e32 v154, v137
	v_cndmask_b32_e32 v138, 0, v131, vcc
	v_cndmask_b32_e64 v139, 0, v131, s[6:7]
	v_cndmask_b32_e64 v140, 0, v131, s[8:9]
	v_cndmask_b32_e64 v141, 0, v131, s[10:11]
	v_cndmask_b32_e64 v151, 0, v131, s[12:13]
	v_ldexp_f32 v134, v89, v138
	v_ldexp_f32 v136, v152, v139
	v_ldexp_f32 v138, v135, v140
	v_ldexp_f32 v137, v153, v141
	v_ldexp_f32 v139, v154, v151
	v_cvt_pk_bf16_f32 v140, v136, v138
	v_cvt_pk_bf16_f32 v141, v137, v139
	v_pk_mul_f32 v[38:39], v[38:39], v[134:135] op_sel_hi:[1,0]
	v_pk_mul_f32 v[36:37], v[36:37], v[134:135] op_sel_hi:[1,0]
	v_pk_mul_f32 v[34:35], v[34:35], v[134:135] op_sel_hi:[1,0]
	v_pk_mul_f32 v[32:33], v[32:33], v[134:135] op_sel_hi:[1,0]
	v_pk_mul_f32 v[30:31], v[30:31], v[134:135] op_sel_hi:[1,0]
	v_pk_mul_f32 v[28:29], v[28:29], v[134:135] op_sel_hi:[1,0]
	v_pk_mul_f32 v[26:27], v[26:27], v[134:135] op_sel_hi:[1,0]
	v_pk_mul_f32 v[24:25], v[24:25], v[134:135] op_sel_hi:[1,0]
	v_mfma_f32_16x16x16_bf16 v[36:39], v[142:143], v[140:141], v[36:39]
	ds_read_b64 v[142:143], v97 offset:45568
	v_pk_mul_f32 v[22:23], v[22:23], v[134:135] op_sel_hi:[1,0]
	v_pk_mul_f32 v[20:21], v[20:21], v[134:135] op_sel_hi:[1,0]
	v_mfma_f32_16x16x16_bf16 v[32:35], v[144:145], v[140:141], v[32:35]
	ds_read_b64 v[144:145], v97 offset:47744
	v_pk_mul_f32 v[10:11], v[10:11], v[134:135] op_sel_hi:[1,0]
	v_pk_mul_f32 v[8:9], v[8:9], v[134:135] op_sel_hi:[1,0]
	v_mfma_f32_16x16x16_bf16 v[28:31], v[146:147], v[140:141], v[28:31]
	ds_read_b64 v[146:147], v97 offset:49920
	v_pk_mul_f32 v[18:19], v[18:19], v[134:135] op_sel_hi:[1,0]
	v_pk_mul_f32 v[16:17], v[16:17], v[134:135] op_sel_hi:[1,0]
	v_mfma_f32_16x16x16_bf16 v[24:27], v[148:149], v[140:141], v[24:27]
	ds_read_b64 v[148:149], v97 offset:52096
	v_pk_mul_f32 v[14:15], v[14:15], v[134:135] op_sel_hi:[1,0]
	v_pk_mul_f32 v[12:13], v[12:13], v[134:135] op_sel_hi:[1,0]
	s_waitcnt lgkmcnt(3)
	v_mfma_f32_16x16x16_bf16 v[20:23], v[142:143], v[140:141], v[20:23]
	v_add_f32_e64 v136, v136, v138
	v_add_f32_e64 v137, v137, v139
	v_add_f32_e32 v89, v136, v137
	s_waitcnt lgkmcnt(2)
	v_mfma_f32_16x16x16_bf16 v[8:11], v[144:145], v[140:141], v[8:11]
	v_fmac_f32_e32 v89, v150, v134
	s_waitcnt lgkmcnt(1)
	v_mfma_f32_16x16x16_bf16 v[16:19], v[146:147], v[140:141], v[16:19]
	s_waitcnt lgkmcnt(0)
	v_mfma_f32_16x16x16_bf16 v[12:15], v[148:149], v[140:141], v[12:15]
	s_cbranch_scc0 .LBB0_1022
	s_waitcnt vmcnt(0)
	v_mov_b64_e32 v[60:61], v[192:193]
	v_mov_b64_e32 v[62:63], v[194:195]
	v_mov_b64_e32 v[56:57], v[196:197]
	v_mov_b64_e32 v[58:59], v[198:199]
	v_mov_b64_e32 v[64:65], v[200:201]
	v_mov_b64_e32 v[66:67], v[202:203]
	v_mov_b64_e32 v[68:69], v[204:205]
	v_mov_b64_e32 v[70:71], v[206:207]
	v_mov_b64_e32 v[40:41], v[208:209]
	v_mov_b64_e32 v[42:43], v[210:211]
	v_mov_b64_e32 v[44:45], v[212:213]
	v_mov_b64_e32 v[46:47], v[214:215]
	v_mov_b64_e32 v[48:49], v[216:217]
	v_mov_b64_e32 v[50:51], v[218:219]
	v_mov_b64_e32 v[52:53], v[220:221]
	v_mov_b64_e32 v[54:55], v[222:223]
	v_add_u32_e32 v94, v80, v98
	s_waitcnt vmcnt(6)
	v_cvt_pk_bf16_f32 v56, v56, v57
	v_cvt_pk_bf16_f32 v57, v58, v59
	v_cvt_pk_bf16_f32 v58, v60, v61
	v_cvt_pk_bf16_f32 v59, v62, v63
	ds_write_b128 v94, v[56:59] offset:18448
	s_waitcnt vmcnt(0)
	v_bfe_u32 v56, v52, 16, 1
	v_cvt_pk_bf16_f32 v68, v68, v69
	v_cvt_pk_bf16_f32 v69, v70, v71
	v_cvt_pk_bf16_f32 v70, v64, v65
	v_cvt_pk_bf16_f32 v71, v66, v67
	v_add3_u32 v52, v52, v56, s45
	ds_write_b128 v94, v[68:71] offset:18432
	ds_write_b16_d16_hi v132, v52 offset:54272
	v_bfe_u32 v52, v53, 16, 1
	v_add3_u32 v52, v53, v52, s45
	ds_write_b16_d16_hi v132, v52 offset:54408
	v_bfe_u32 v52, v54, 16, 1
	v_add3_u32 v52, v54, v52, s45
	ds_write_b16_d16_hi v132, v52 offset:54544
	v_bfe_u32 v52, v55, 16, 1
	v_add3_u32 v52, v55, v52, s45
	ds_write_b16_d16_hi v132, v52 offset:54680
	v_bfe_u32 v52, v48, 16, 1
	v_add3_u32 v48, v48, v52, s45
	ds_write_b16_d16_hi v132, v48 offset:54816
	v_bfe_u32 v48, v49, 16, 1
	v_add3_u32 v48, v49, v48, s45
	ds_write_b16_d16_hi v132, v48 offset:54952
	v_bfe_u32 v48, v50, 16, 1
	v_add3_u32 v48, v50, v48, s45
	ds_write_b16_d16_hi v132, v48 offset:55088
	v_bfe_u32 v48, v51, 16, 1
	v_add3_u32 v48, v51, v48, s45
	ds_write_b16_d16_hi v132, v48 offset:55224
	v_bfe_u32 v48, v44, 16, 1
	v_add3_u32 v44, v44, v48, s45
	ds_write_b16_d16_hi v132, v44 offset:55360
	v_bfe_u32 v44, v45, 16, 1
	v_add3_u32 v44, v45, v44, s45
	ds_write_b16_d16_hi v132, v44 offset:55496
	v_bfe_u32 v44, v46, 16, 1
	v_add3_u32 v44, v46, v44, s45
	ds_write_b16_d16_hi v132, v44 offset:55632
	v_bfe_u32 v44, v47, 16, 1
	v_add3_u32 v44, v47, v44, s45
	ds_write_b16_d16_hi v132, v44 offset:55768
	v_bfe_u32 v44, v40, 16, 1
	v_add3_u32 v40, v40, v44, s45
	ds_write_b16_d16_hi v132, v40 offset:55904
	v_bfe_u32 v40, v41, 16, 1
	v_add3_u32 v40, v41, v40, s45
	v_or_b32_e32 v92, s33, v100
	ds_write_b16_d16_hi v132, v40 offset:56040
	v_bfe_u32 v40, v42, 16, 1
	v_ashrrev_i32_e32 v93, 31, v92
	v_add3_u32 v40, v42, v40, s45
	v_lshlrev_b64 v[92:93], 12, v[92:93]
	ds_write_b16_d16_hi v132, v40 offset:56176
	v_bfe_u32 v40, v43, 16, 1
	v_lshl_add_u64 v[96:97], s[22:23], 0, v[92:93]
	v_add3_u32 v40, v43, v40, s45
	ds_write_b16_d16_hi v132, v40 offset:56312
	v_lshl_add_u64 v[40:41], v[96:97], 0, s[38:39]
	v_lshl_add_u64 v[62:63], v[40:41], 0, v[74:75]
	v_mov_b32_e32 v40, 0
	v_mov_b32_e32 v44, 0
	v_mov_b32_e32 v45, 0
	v_mov_b32_e32 v46, 0
	v_mov_b32_e32 v47, 0
	s_waitcnt lgkmcnt(0)
	s_barrier
	s_and_saveexec_b64 s[6:7], s[2:3]
	s_cbranch_execz .LBB0_1025
	global_load_dwordx4 v[44:47], v[62:63], off
